# lever 4 mirrored: one static s_setprio 1 per GEMM unit for the leading (older, waves 0-3) half, all per-segment flips deleted
# speedup vs baseline: 1.0065x; 1.0065x over previous
;     __device__ __forceinline__ bool next(int i, Unit& u) const { if (!base.next(i >> 1, u)) return false; if (i & 1) { u.pm += 64; u.pn += 8; } return true; }
; template <class Epi, class Sched, bool ALIGN_EPI = false, bool SP2 = false>
; __device__ __forceinline__ void gemm_phase(PG8_LAS unsigned char* lds, const Gemm g, const Sched& S, const Epi& E) {
;     ...
;         const bool has_next = S.next(ui + 1, nxt);
;         const char* nA = has_next ? (const char*)g.A + (size_t)nxt.pm * tstep : cA; const char* nB = has_next ? (const char*)g.Bt + (size_t)nxt.pn * tstep : cB;
;         for (int t = 0; t < nt; t += 2) {
;             const bool last = (t == nt - 2);
;             const char* a1 = cA + (size_t)(t + 1) * kstep;
;             const char* a2 = last ? nA : cA + (size_t)(t + 2) * kstep; const char* b2 = last ? nB : cB + (size_t)(t + 2) * kstep;
;             const char* a3 = a2 + kstep; const char* b3 = b2 + kstep;
;             if (last && has_next) S.a_ready(nxt);
.LBB0_204:
	s_ashr_i32 s21, s20, 31
	s_lshl_b64 s[24:25], s[20:21], 20
	v_readlane_b32 s26, v236, 50
	v_readlane_b32 s27, v236, 51
	s_add_u32 s24, s26, s24
	s_addc_u32 s25, s27, s25
	s_and_b64 s[26:27], s[8:9], exec
	s_cselect_b32 s1, s25, s5
	s_cselect_b32 s3, s24, s4
	s_ashr_i32 s23, s22, 31
	s_lshl_b64 s[26:27], s[22:23], 20
	s_add_u32 s26, s10, s26
	s_addc_u32 s27, s11, s27
	s_and_b64 s[28:29], s[8:9], exec
	s_cselect_b32 s21, s27, s7
	s_cselect_b32 s23, s26, s6
	s_add_u32 s4, s4, 0x80080
	s_addc_u32 s5, s5, 0
	s_add_u32 s33, s6, 0x100
	s_addc_u32 s50, s7, 0
	s_mov_b32 s51, -2
	s_waitcnt vmcnt(0)
	s_cmp_eq_u64 s[18:19], 0
	s_cbranch_scc1 .Lprio_skip_205
	s_setprio 1

;     __device__ __forceinline__ bool next(int i, Unit& u) const { if (!base.next(i >> 1, u)) return false; if (i & 1) { u.pm += 64; u.pn += 8; } return true; }
; template <class Epi, class Sched, bool ALIGN_EPI = false, bool SP2 = false>
; __device__ __forceinline__ void gemm_phase(PG8_LAS unsigned char* lds, const Gemm g, const Sched& S, const Epi& E) {
;     ...
;         const bool has_next = S.next(ui + 1, nxt);
;         const char* nA = has_next ? (const char*)g.A + (size_t)nxt.pm * tstep : cA; const char* nB = has_next ? (const char*)g.Bt + (size_t)nxt.pn * tstep : cB;
;         for (int t = 0; t < nt; t += 2) {
;             const bool last = (t == nt - 2);
;             const char* a1 = cA + (size_t)(t + 1) * kstep;
;             const char* a2 = last ? nA : cA + (size_t)(t + 2) * kstep; const char* b2 = last ? nB : cB + (size_t)(t + 2) * kstep;
;             const char* a3 = a2 + kstep; const char* b3 = b2 + kstep;
;             if (last && has_next) S.a_ready(nxt);
.LBB0_571:
	s_bitcmp0_b32 s7, 0
	s_cselect_b64 s[16:17], -1, 0
	s_and_b64 s[16:17], s[16:17], s[4:5]
	s_add_i32 s7, s14, 64
	s_add_i32 s13, s12, 8
	s_and_b64 s[16:17], s[16:17], exec
	s_cselect_b32 s14, s7, s14
	s_cselect_b32 s12, s13, s12
	s_ashr_i32 s15, s14, 31
	s_lshl_b64 s[16:17], s[14:15], 19
	s_add_u32 s16, s29, s16
	s_addc_u32 s17, s30, s17
	s_and_b64 s[18:19], s[4:5], exec
	s_cselect_b32 s7, s17, s23
	s_cselect_b32 s15, s16, s22
	s_ashr_i32 s13, s12, 31
	s_lshl_b64 s[18:19], s[12:13], 19
	v_readlane_b32 s26, v236, 41
	v_readlane_b32 s27, v236, 42
	s_add_u32 s18, s26, s18
	s_addc_u32 s19, s27, s19
	s_and_b64 s[26:27], s[4:5], exec
	s_cselect_b32 s13, s19, s25
	s_cselect_b32 s21, s18, s24
	s_add_u32 s22, s22, 0x40080
	s_addc_u32 s23, s23, 0
	s_add_u32 s44, s24, 0x100
	s_addc_u32 s45, s25, 0
	s_mov_b32 s46, -2
	s_cmp_eq_u64 s[10:11], 0
	s_cbranch_scc1 .Lprio_skip_572
	s_setprio 1

;     __device__ __forceinline__ bool next(int i, Unit& u) const { if (!base.next(i >> 1, u)) return false; if (i & 1) { u.pm += 64; u.pn += 8; } return true; }
; template <class Epi, class Sched, bool ALIGN_EPI = false, bool SP2 = false>
; __device__ __forceinline__ void gemm_phase(PG8_LAS unsigned char* lds, const Gemm g, const Sched& S, const Epi& E) {
;     ...
;         const bool has_next = S.next(ui + 1, nxt);
;         const char* nA = has_next ? (const char*)g.A + (size_t)nxt.pm * tstep : cA; const char* nB = has_next ? (const char*)g.Bt + (size_t)nxt.pn * tstep : cB;
;         for (int t = 0; t < nt; t += 2) {
;             const bool last = (t == nt - 2);
;             const char* a1 = cA + (size_t)(t + 1) * kstep;
;             const char* a2 = last ? nA : cA + (size_t)(t + 2) * kstep; const char* b2 = last ? nB : cB + (size_t)(t + 2) * kstep;
;             const char* a3 = a2 + kstep; const char* b3 = b2 + kstep;
;             if (last && has_next) S.a_ready(nxt);
.LBB0_893:
	s_ashr_i32 s25, s24, 31
	s_lshl_b64 s[28:29], s[24:25], 20
	v_readlane_b32 s30, v236, 50
	v_readlane_b32 s31, v236, 51
	s_add_u32 s28, s30, s28
	s_addc_u32 s29, s31, s29
	s_and_b64 s[30:31], s[6:7], exec
	s_cselect_b32 s25, s29, s39
	s_cselect_b32 s35, s28, s38
	s_ashr_i32 s27, s26, 31
	s_lshl_b64 s[30:31], s[26:27], 20
	v_readlane_b32 s42, v236, 43
	v_readlane_b32 s43, v236, 44
	s_add_u32 s30, s42, s30
	s_addc_u32 s31, s43, s31
	s_and_b64 s[42:43], s[6:7], exec
	s_cselect_b32 s27, s31, s41
	s_cselect_b32 s55, s30, s40
	s_add_u32 s38, s38, 0x80080
	s_addc_u32 s39, s39, 0
	s_add_u32 s56, s40, 0x100
	s_addc_u32 s57, s41, 0
	s_mov_b32 s58, -2
	s_waitcnt lgkmcnt(0)
	s_cmp_eq_u64 s[14:15], 0
	s_cbranch_scc1 .Lprio_skip_894
	s_setprio 1

;     __device__ __forceinline__ bool next(int i, Unit& u) const { if (!base.next(i >> 1, u)) return false; if (i & 1) { u.pm += 64; u.pn += 8; } return true; }
; template <class Epi, class Sched, bool ALIGN_EPI = false, bool SP2 = false>
; __device__ __forceinline__ void gemm_phase(PG8_LAS unsigned char* lds, const Gemm g, const Sched& S, const Epi& E) {
;     ...
;         const bool has_next = S.next(ui + 1, nxt);
;         const char* nA = has_next ? (const char*)g.A + (size_t)nxt.pm * tstep : cA; const char* nB = has_next ? (const char*)g.Bt + (size_t)nxt.pn * tstep : cB;
;         for (int t = 0; t < nt; t += 2) {
;             const bool last = (t == nt - 2);
;             const char* a1 = cA + (size_t)(t + 1) * kstep;
;             const char* a2 = last ? nA : cA + (size_t)(t + 2) * kstep; const char* b2 = last ? nB : cB + (size_t)(t + 2) * kstep;
;             const char* a3 = a2 + kstep; const char* b3 = b2 + kstep;
;             if (last && has_next) S.a_ready(nxt);
.LBB0_993:
	s_ashr_i32 s15, s14, 31
	s_lshl_b64 s[18:19], s[14:15], 20
	s_add_u32 s18, s8, s18
	s_addc_u32 s19, s9, s19
	s_and_b64 s[20:21], s[4:5], exec
	s_cselect_b32 s15, s19, s25
	s_cselect_b32 s43, s18, s24
	s_ashr_i32 s17, s16, 31
	s_lshl_b64 s[20:21], s[16:17], 20
	v_readlane_b32 s28, v236, 52
	v_readlane_b32 s29, v236, 53
	s_add_u32 s20, s28, s20
	s_addc_u32 s21, s29, s21
	s_and_b64 s[28:29], s[4:5], exec
	s_cselect_b32 s17, s21, s27
	s_cselect_b32 s44, s20, s26
	s_add_u32 s24, s24, 0x80080
	s_addc_u32 s25, s25, 0
	s_add_u32 s45, s26, 0x100
	s_addc_u32 s46, s27, 0
	s_mov_b32 s47, -2
	s_cmp_eq_u64 s[12:13], 0
	s_cbranch_scc1 .Lprio_skip_994
	s_setprio 1

;     __device__ __forceinline__ bool next(int i, Unit& u) const { if (!base.next(i >> 1, u)) return false; if (i & 1) { u.pm += 64; u.pn += 8; } return true; }
; template <class Epi, class Sched, bool ALIGN_EPI = false, bool SP2 = false>
; __device__ __forceinline__ void gemm_phase(PG8_LAS unsigned char* lds, const Gemm g, const Sched& S, const Epi& E) {
;     ...
;         const bool has_next = S.next(ui + 1, nxt);
;         const char* nA = has_next ? (const char*)g.A + (size_t)nxt.pm * tstep : cA; const char* nB = has_next ? (const char*)g.Bt + (size_t)nxt.pn * tstep : cB;
;         for (int t = 0; t < nt; t += 2) {
;             const bool last = (t == nt - 2);
;             const char* a1 = cA + (size_t)(t + 1) * kstep;
;             const char* a2 = last ? nA : cA + (size_t)(t + 2) * kstep; const char* b2 = last ? nB : cB + (size_t)(t + 2) * kstep;
;             const char* a3 = a2 + kstep; const char* b3 = b2 + kstep;
;             if (last && has_next) S.a_ready(nxt);
.LBB0_1070:
	s_ashr_i32 s19, s18, 31
	s_lshl_b64 s[20:21], s[18:19], 22
	s_add_u32 s20, s72, s20
	s_addc_u32 s21, s73, s21
	s_and_b64 s[22:23], s[0:1], exec
	s_cselect_b32 s19, s21, s27
	s_cselect_b32 s51, s20, s26
	s_ashr_i32 s17, s16, 31
	s_lshl_b64 s[22:23], s[16:17], 22
	v_readlane_b32 s30, v236, 54
	v_readlane_b32 s31, v236, 55
	s_add_u32 s22, s30, s22
	s_addc_u32 s23, s31, s23
	s_and_b64 s[30:31], s[0:1], exec
	s_cselect_b32 s17, s23, s29
	s_cselect_b32 s52, s22, s28
	s_add_u32 s26, s26, 0x200080
	s_addc_u32 s27, s27, 0
	s_add_u32 s53, s28, 0x100
	s_addc_u32 s54, s29, 0
	s_mov_b32 s55, -2
	s_cmp_eq_u64 s[6:7], 0
	s_cbranch_scc1 .Lprio_skip_1071
	s_setprio 1
